# FFN up->down barriers (P2|P3, P11|P12) XCD-local: run-time check that the 32 workgroups with equal blockIdx%8 share one XCC (published ids compared after the first barrier), else full barrier
# speedup vs baseline: 1.0084x; 1.0084x over previous
; __device__ __forceinline__ int lane_now() { int l; asm volatile("v_mbcnt_lo_u32_b32 %0, -1, 0\n\tv_mbcnt_hi_u32_b32 %0, -1, %0" : "=v"(l)); return l; }
; #define LAS __attribute__((address_space(3)))
; __device__ __forceinline__ unsigned xb_add(unsigned* p, unsigned v) { return __hip_atomic_fetch_add(p, v, __ATOMIC_RELAXED, __HIP_MEMORY_SCOPE_AGENT); }
; __device__ __forceinline__ unsigned xb_xcc_id() { return (unsigned)__builtin_amdgcn_s_getreg((3 << 11) | 20) & 0xFu; }
; __device__ __forceinline__ XcdBarrier xcd_barrier_post(unsigned* bar, volatile LAS unsigned* st, unsigned w0) {
;     XcdBarrier b; b.w0 = w0; b.bar = bar; b.x = xb_xcc_id(); b.st = st;
;     if (w0 && lane_now() == 0) (void)xb_add(&bar[XB_XCNT(b.x)], 1u);
;     return b;
; }
; __global__ void __launch_bounds__(512, 2) mega_fwd(Params p) {
;     ...
;     { const int t0_ = tid; if (t0_ < 2) *(LAS unsigned*)(lds + LDS_BYTES - 64 + 4 * t0_) = 0u; }
;     __syncthreads();
;     const XcdBarrier xbar = xcd_barrier_post((unsigned*)(ws + WS_BAR), (volatile LAS unsigned*)(lds + LDS_BYTES - 64), wave == 0 ? 1u : 0u);
_Z8mega_fwd6Params:
	s_load_dwordx8 s[88:95], s[0:1], 0xe0
	s_load_dwordx8 s[12:19], s[0:1], 0xc0
	v_writelane_b32 v244, s2, 0
	s_load_dword s2, s[0:1], 0x100
	v_and_b32_e32 v1, 0x3ff, v0
	s_add_u32 s6, s0, 0xf8
	s_addc_u32 s7, s1, 0
	v_mbcnt_lo_u32_b32 v2, -1, 0
	v_mbcnt_hi_u32_b32 v2, -1, v2
	s_waitcnt lgkmcnt(0)
	v_writelane_b32 v244, s2, 1
	v_readfirstlane_b32 s2, v1
	s_and_b32 s86, s2, 0xffffffc0
	v_add_u32_e32 v2, s86, v2
	v_cmp_gt_i32_e32 vcc, 2, v2
	v_writelane_b32 v244, s2, 2
	s_and_saveexec_b64 s[2:3], vcc
	v_lshl_add_u32 v2, v2, 2, 0
	v_add_u32_e32 v2, 0x23fc0, v2
	v_mov_b32_e32 v3, 0
	ds_write_b32 v2, v3
	s_or_b64 exec, exec, s[2:3]
	s_add_u32 s2, s92, 0xc0000
	s_addc_u32 s3, s93, 0
	v_writelane_b32 v244, s2, 3
	s_waitcnt lgkmcnt(0)
	s_barrier
	v_writelane_b32 v244, s3, 4
	s_nop 0
	v_readlane_b32 s4, v244, 2
	s_cmp_lt_u32 s4, 64
	s_getreg_b32 s87, hwreg(HW_REG_XCC_ID, 0, 4)
	s_cselect_b64 s[2:3], -1, 0
	s_and_b32 s5, s87, 15
	s_cmp_gt_u32 s4, 63
	v_writelane_b32 v244, s5, 5
	s_cbranch_scc1 .LBB0_7
	v_mbcnt_lo_u32_b32 v2, -1, 0
	v_mbcnt_hi_u32_b32 v2, -1, v2
	s_nop 0
	v_cmp_eq_u32_e32 vcc, 0, v2
	s_and_saveexec_b64 s[4:5], vcc
	s_cbranch_execz .LBB0_6
	s_mov_b64 s[8:9], exec
	v_mbcnt_lo_u32_b32 v2, s8, 0
	v_mbcnt_hi_u32_b32 v2, s9, v2
	v_cmp_eq_u32_e32 vcc, 0, v2
	s_and_b64 s[10:11], exec, vcc
	s_mov_b64 exec, s[10:11]
	s_cbranch_execz .LBB0_6
	v_readlane_b32 s10, v244, 5
	s_bcnt1_i32_b64 s8, s[8:9]
	s_lshl_b32 s10, s10, 8
	v_mov_b32_e32 v3, s8
	v_readlane_b32 s8, v244, 3
	v_mov_b32_e32 v2, s10
	v_readlane_b32 s9, v244, 4
	s_nop 4
	global_atomic_add v2, v3, s[8:9] offset:1024
	v_readlane_b32 s10, v244, 0
	s_cmp_gt_u32 s10, 7
	s_cbranch_scc1 .Lxl_nopub
	v_readlane_b32 s11, v244, 5
	s_add_i32 s11, s11, 1
	s_lshl_b32 s10, s10, 2
	s_add_i32 s10, s10, 0x3f00
	v_mov_b32_e32 v2, s10
	v_mov_b32_e32 v3, s11
	global_atomic_add v2, v3, s[8:9]

; #define LAS __attribute__((address_space(3)))
; #define BAR_LDS() do { asm volatile("s_waitcnt lgkmcnt(0)" ::: "memory"); __builtin_amdgcn_s_barrier(); asm volatile("" ::: "memory"); } while (0)
; #define lane (lane_now())
; __device__ __forceinline__ void norm_phase(const float* src, const float* g, const float* mod, int ish, int isc, bf16_t* dst, LAS unsigned char* lds, int gw, int ngw, int wave, int lane) {
;     LAS float* GSl = (LAS float*)lds; LAS float* SHl = GSl + 4096;
;     for (int i = wave * 64 + lane; i < 4096; i += 512) { const int b = i >> 10, c = i & 1023; GSl[i] = g[c] * (1.f + mod[(size_t)b * NMOD + isc * 1024 + c]); SHl[i] = mod[(size_t)b * NMOD + ish * 1024 + c]; }
;     BAR_LDS();
; __global__ void __launch_bounds__(512, 2) mega_fwd(Params p) {
;     ...
;     grid.sync();
;     norm_phase(p.x, p.norm1_g, mod, 0, 1, XN, lds, gw, ngw, wave, lane);
;     xcd_barrier(xbar);
.Lgb0_141:
	s_mov_b64 exec, -1
	v_readlane_b32 s0, v245, 0
	v_readlane_b32 s1, v245, 1
	v_readlane_b32 s2, v245, 2
	v_readlane_b32 s3, v245, 3
	v_readlane_b32 s4, v245, 4
	v_readlane_b32 s5, v245, 5
	v_readlane_b32 s6, v245, 6
	v_readlane_b32 s7, v245, 7
	v_readlane_b32 s8, v245, 8
	v_readlane_b32 s9, v245, 9
	v_readlane_b32 s10, v245, 10
	v_readlane_b32 s11, v245, 11
	v_readlane_b32 s12, v245, 12
	v_readlane_b32 s13, v245, 13
	v_readlane_b32 s14, v245, 14
	v_readlane_b32 s15, v245, 15
	v_readlane_b32 s16, v245, 16
	v_readlane_b32 s17, v245, 17
	v_readlane_b32 s18, v245, 18
	v_readlane_b32 s19, v245, 19
	v_readlane_b32 s20, v245, 20
	v_readlane_b32 s21, v245, 21
	v_readlane_b32 s22, v245, 22
	v_readlane_b32 s23, v245, 23
	v_readlane_b32 s24, v245, 24
	v_readlane_b32 s25, v245, 25
	v_readlane_b32 s26, v245, 26
	v_readlane_b32 s27, v245, 27
	v_readlane_b32 s28, v245, 28
	v_readlane_b32 s29, v245, 29
	v_readlane_b32 s30, v245, 30
	v_readlane_b32 s31, v245, 31
	v_readlane_b32 s32, v245, 32
	v_readlane_b32 s33, v245, 33
	v_readlane_b32 s34, v245, 34
	v_readlane_b32 s35, v245, 35
	v_readlane_b32 s36, v245, 36
	v_readlane_b32 s37, v245, 37
	v_readlane_b32 s38, v245, 38
	v_readlane_b32 s39, v245, 39
	v_readlane_b32 s40, v245, 40
	v_readlane_b32 s41, v245, 41
	v_readlane_b32 s42, v245, 42
	v_readlane_b32 s43, v245, 43
	v_readlane_b32 s44, v245, 44
	v_readlane_b32 s45, v245, 45
	v_readlane_b32 s46, v245, 46
	v_readlane_b32 s47, v245, 47
	v_readlane_b32 s48, v245, 48
	v_readlane_b32 s49, v245, 49
	v_readlane_b32 s50, v245, 50
	v_readlane_b32 s51, v245, 51
	v_readlane_b32 s52, v245, 52
	v_readlane_b32 s53, v245, 53
	v_readlane_b32 s54, v245, 54
	v_readlane_b32 s55, v245, 55
	v_readlane_b32 s56, v245, 56
	v_readlane_b32 s57, v245, 57
	v_readlane_b32 s58, v245, 58
	v_readlane_b32 s59, v245, 59
	v_readlane_b32 s60, v245, 60
	v_readlane_b32 s61, v245, 61
	v_readlane_b32 s62, v245, 62
	v_readlane_b32 s63, v245, 63
	v_readlane_b32 s64, v246, 0
	v_readlane_b32 s65, v246, 1
	v_readlane_b32 s66, v246, 2
	v_readlane_b32 s67, v246, 3
	v_readlane_b32 s68, v246, 4
	v_readlane_b32 s69, v246, 5
	v_readlane_b32 s70, v246, 6
	v_readlane_b32 s71, v246, 7
	v_readlane_b32 s72, v246, 8
	v_readlane_b32 s73, v246, 9
	v_readlane_b32 s74, v246, 10
	v_readlane_b32 s75, v246, 11
	v_readlane_b32 s76, v246, 12
	v_readlane_b32 s77, v246, 13
	v_readlane_b32 s78, v246, 14
	v_readlane_b32 s79, v246, 15
	v_readlane_b32 s80, v246, 16
	v_readlane_b32 s81, v246, 17
	v_readlane_b32 s82, v246, 18
	v_readlane_b32 s83, v246, 19
	v_readlane_b32 s84, v246, 20
	v_readlane_b32 s85, v246, 21
	v_readlane_b32 s86, v246, 22
	v_readlane_b32 s87, v246, 23
	v_readlane_b32 s88, v246, 24
	v_readlane_b32 s89, v246, 25
	v_readlane_b32 s90, v246, 26
	v_readlane_b32 s91, v246, 27
	v_readlane_b32 s92, v246, 28
	v_readlane_b32 s93, v246, 29
	v_readlane_b32 s94, v246, 30
	v_readlane_b32 s95, v246, 31
	v_readlane_b32 s96, v246, 32
	v_readlane_b32 s97, v246, 33
	v_readlane_b32 vcc_lo, v246, 34
	v_readlane_b32 vcc_hi, v246, 35
	s_nop 7
	s_barrier
	v_readlane_b32 s100, v244, 0
	s_and_b32 s100, s100, 7
	s_lshl_b32 s100, s100, 2
	s_add_i32 s100, s100, 0xc3f00
	v_mov_b32_e32 v245, s100
	global_load_dword v245, v245, s[92:93] sc1
	v_readlane_b32 s101, v244, 5
	s_add_i32 s101, s101, 1
	s_waitcnt vmcnt(0)
	v_readfirstlane_b32 s100, v245
	s_cmp_eq_u32 s100, s101
	s_cbranch_scc1 .Lxl_same
	s_mov_b64 exec, 1
	v_mov_b32_e32 v245, 0xc3e80
	v_mov_b32_e32 v246, 1
	global_atomic_add v245, v246, s[92:93]
	s_mov_b64 exec, -1
.Lxl_same:
	v_mbcnt_lo_u32_b32 v0, -1, 0
	v_mbcnt_hi_u32_b32 v0, -1, v0
	s_movk_i32 s0, 0x1000
	v_add_u32_e32 v2, s86, v0
	v_cmp_gt_i32_e32 vcc, s0, v2
	s_and_saveexec_b64 s[6:7], vcc
	s_cbranch_execz .LBB0_84
	v_max_i32_e32 v1, 0xe00, v2
	v_sub_u32_e32 v1, v1, v2
	v_add_u32_e32 v3, 0x1ff, v1
	s_movk_i32 s0, 0xa00
	v_cmp_gt_u32_e64 s[10:11], s0, v3
	s_movk_i32 s0, 0x9ff
	v_cmp_lt_u32_e32 vcc, s0, v3
	s_and_saveexec_b64 s[16:17], vcc
	s_cbranch_execz .LBB0_81
	v_readlane_b32 s0, v244, 2
	v_lshrrev_b32_e32 v1, 9, v3
	s_and_b32 s0, s0, 0x3c0
	v_add_u16_e32 v4, s0, v0
	v_and_b32_e32 v5, 0x3ff, v1
	v_lshlrev_b16_e32 v6, 9, v1
	s_mov_b32 s4, 0x80000
	v_and_b32_e32 v4, 0x3ff, v4
	v_and_b32_e32 v6, 0x200, v6
	v_cmp_gt_u16_e32 vcc, 2, v5
	v_cmp_gt_u32_e64 s[4:5], s4, v3
	v_cmp_le_u16_e64 s[0:1], v6, v4
	s_and_b64 s[4:5], vcc, s[4:5]
	s_and_b64 s[20:21], s[4:5], s[0:1]
	s_mov_b64 s[4:5], -1
	s_and_saveexec_b64 s[0:1], s[20:21]
	s_cbranch_execz .LBB0_80
	v_add_u32_e32 v3, 0x200, v2
	v_add_u32_e32 v8, -1, v1
	v_cmp_lt_u32_e32 vcc, 1, v8
	v_mov_b32_e32 v6, 0
	v_mov_b64_e32 v[4:5], v[2:3]
	s_and_saveexec_b64 s[4:5], vcc
	s_cbranch_execz .LBB0_77
	v_lshrrev_b32_e32 v4, 1, v8
	s_lshl_b32 s20, s83, 8
	v_add_u32_e32 v4, 1, v4
	s_add_i32 s20, s20, 0
	v_and_b32_e32 v9, -2, v4
	s_mov_b32 s22, 0
	v_lshl_add_u32 v10, v0, 2, s20
	s_mov_b64 s[20:21], 0
	v_mov_b32_e32 v7, 0
	s_movk_i32 s23, 0x1000
	v_mov_b64_e32 v[4:5], v[2:3]

; __device__ __forceinline__ int lane_now() { int l; asm volatile("v_mbcnt_lo_u32_b32 %0, -1, 0\n\tv_mbcnt_hi_u32_b32 %0, -1, %0" : "=v"(l)); return l; }
; #define PG8_WAIT_V(n) asm volatile("s_waitcnt vmcnt(" #n ")" ::: "memory")
; #define lane (lane_now())
; template <class Epi, class Sched, bool ALIGN_EPI = false, bool SP2 = false>
; __device__ __forceinline__ void gemm_phase(PG8_LAS unsigned char* lds, const Gemm g, const Sched& S, const Epi& E, const int wid) {
;     const int lane = lane_now(), tid = wid * 64 + lane, wr = wid >> 2, wc = wid & 3, fr = lane & 15, fq = lane >> 4;
;     const int K = g.K, nt = K / BK;
;     unsigned voffA[2], voffB[2];
; #pragma unroll
;     for (int i = 0; i < 2; ++i) { int R, C; stage_rc(tid * 16 + i * 8192, R, C); const int Rb = Epi::PERM ? ((R & ~31) + perm32(R & 31)) : R;
;         voffA[i] = (unsigned)(R * K + C) * 2u; voffB[i] = (unsigned)(Rb * K + C) * 2u; }
;     const size_t kstep = (size_t)(BK * 2);
;     const size_t hstep = (size_t)HALF * K * 2;
;     const size_t tstep = 2 * hstep;
;     const unsigned ldsw = (unsigned)wid * 1024u;
;     const int aoff = lds_byte(wr * 64 + fr, fq * 8), boff = lds_byte(wc * 32 + fr, fq * 8);
;     ...
;     Unit cur, nxt; int ui = 0;
;     if (!S.next(0, cur)) return;
;     f32x4 acc[2][2][4][2];
; #pragma unroll
;     for (int a = 0; a < 2; ++a)
; #pragma unroll
;         for (int b = 0; b < 2; ++b)
; #pragma unroll
;             for (int m = 0; m < 4; ++m)
; #pragma unroll
;                 for (int n = 0; n < 2; ++n) acc[a][b][m][n] = (f32x4){0.f, 0.f, 0.f, 0.f};
;     bf16x8 At[4][2], B0[2][2], B1[2][2];
;     const char* cA = (const char*)g.A + (size_t)cur.pm * tstep; const char* cB = (const char*)g.Bt + (size_t)cur.pn * tstep;
;     S.a_ready(cur);
;     if constexpr (SP2) {
;         PG8_STAGE(PG8_SB(0, 0), cB, voffB); PG8_STAGE(PG8_SB(0, 1), cB + hstep, voffB); PG8_STAGE(PG8_SA(0, 0), cA, voffA); PG8_STAGE(PG8_SA(0, 1), cA + hstep, voffA);
;         if (wr == 1) PG8_BAR;
;         PG8_WAIT_V(2); PG8_BAR;
;         PG8_STAGE(PG8_SB(1, 0), cB + kstep, voffB); PG8_STAGE(PG8_SA(1, 0), cA + kstep, voffA); PG8_STAGE(PG8_SB(1, 1), cB + hstep + kstep, voffB);
;         PG8_WAIT_V(6); PG8_BAR;
;     } else {
;         PG8_STAGE(PG8_SB(0, 0), cB, voffB); PG8_STAGE(PG8_SA(0, 0), cA, voffA); PG8_STAGE(PG8_SB(0, 1), cB + hstep, voffB); PG8_STAGE(PG8_SA(0, 1), cA + hstep, voffA);
.LBB0_141:
	v_mov_b32_e32 v245, 0xc3e80
	global_load_dword v245, v245, s[92:93] sc1
	s_waitcnt vmcnt(0)
	v_readfirstlane_b32 s100, v245
	s_cmp_eq_u32 s100, 0
	s_cselect_b32 s100, 1, 0
	s_cmp_eq_u32 s94, 0x100
	s_cselect_b32 s100, s100, 0
	v_writelane_b32 v244, s100, 61
	s_add_u32 s2, s92, 0x2b00000
	s_addc_u32 s3, s93, 0
	s_add_u32 s96, s92, 0x6b00000
	v_readlane_b32 s4, v244, 2
	s_addc_u32 s97, s93, 0
	s_lshr_b32 s5, s4, 8
	s_lshl_b32 s4, s5, 6
	v_writelane_b32 v244, s4, 17
	v_writelane_b32 v244, s5, 18
	s_lshl_b32 s4, s5, 13
	v_writelane_b32 v244, s4, 19
	s_lshl_b32 s4, s83, 5
	v_writelane_b32 v244, s4, 20
	s_and_b32 s4, s4, 0x60
	s_lshl_b32 s33, s83, 10
	v_writelane_b32 v244, s4, 21
	s_lshr_b32 s4, s4, 3
	s_cmpk_lt_i32 s82, 0xb00
	v_writelane_b32 v244, s4, 22
	s_cselect_b64 s[4:5], -1, 0
	v_writelane_b32 v244, s4, 23
	s_cmpk_gt_i32 s82, 0xaff
	s_waitcnt lgkmcnt(0)
	s_barrier
	v_writelane_b32 v244, s5, 24
	v_mbcnt_lo_u32_b32 v10, -1, 0
	v_mbcnt_hi_u32_b32 v10, -1, v10
	s_cbranch_scc1 .LBB0_157
	v_lshl_add_u32 v0, v10, 4, s33
	v_add_u32_e32 v1, 0x2000, v0
	v_ashrrev_i32_e32 v2, 31, v1
	v_lshrrev_b32_e32 v2, 22, v2
	v_add_u32_e32 v2, v1, v2
	v_ashrrev_i32_e32 v8, 10, v2
	v_mul_i32_i24_e32 v2, 0x400, v8
	v_sub_u32_e32 v1, v1, v2
	v_lshrrev_b32_e32 v2, 4, v1
	v_bitop3_b32 v1, v2, v1, 32 bitop3:0x6c
	v_ashrrev_i32_e32 v2, 31, v1
	v_lshrrev_b32_e32 v2, 26, v2
	v_add_u32_e32 v2, v1, v2
	v_ashrrev_i32_e32 v9, 6, v2
	v_lshlrev_b32_e32 v3, 3, v8
	v_and_b32_e32 v2, 0xffc0, v2
	v_and_b32_e32 v3, -16, v3
	v_sub_u32_e32 v1, v1, v2
	v_add_u32_e32 v3, v9, v3
	v_lshrrev_b16_e32 v2, 7, v1
	v_and_b32_e32 v4, 3, v9
	s_mov_b32 s4, 0x1fffe0
	v_lshrrev_b32_e32 v5, 2, v3
	v_lshlrev_b32_e32 v6, 1, v3
	v_and_b32_e32 v2, 1, v2
	v_and_or_b32 v4, v3, s4, v4
	v_and_b32_e32 v5, 4, v5
	v_and_b32_e32 v6, 24, v6
	v_add_u16_e32 v1, v1, v2
	v_mov_b32_e32 v2, 1
	v_or3_b32 v4, v4, v5, v6
	v_lshlrev_b32_e32 v5, 5, v8
	v_ashrrev_i16_sdwa v1, v2, sext(v1) dst_sel:DWORD dst_unused:UNUSED_PAD src0_sel:DWORD src1_sel:BYTE_0
	v_and_b32_e32 v5, 32, v5
	v_bfe_i32 v11, v1, 0, 16
	v_add_lshl_u32 v1, v5, v11, 1
	v_lshl_add_u32 v128, v4, 11, v1
	v_lshl_add_u32 v130, v3, 11, v1
	v_ashrrev_i32_e32 v1, 31, v0
	v_lshrrev_b32_e32 v1, 22, v1
	v_add_u32_e32 v1, v0, v1
	v_ashrrev_i32_e32 v12, 10, v1
	v_mul_i32_i24_e32 v1, 0x400, v12
	v_sub_u32_e32 v0, v0, v1
	v_lshrrev_b32_e32 v1, 4, v0
	v_bitop3_b32 v0, v1, v0, 32 bitop3:0x6c
	v_ashrrev_i32_e32 v1, 31, v0
	v_lshrrev_b32_e32 v1, 26, v1
	v_add_u32_e32 v1, v0, v1
	v_lshlrev_b32_e32 v3, 3, v12
	s_add_u32 s40, s92, 0x100000
	v_ashrrev_i32_e32 v13, 6, v1
	v_and_b32_e32 v3, -16, v3
	s_addc_u32 s41, s93, 0
	v_add_u32_e32 v3, v13, v3
	v_and_b32_e32 v4, 3, v13
	s_ashr_i32 s42, s82, 31
	v_and_or_b32 v4, v3, s4, v4
	s_lshr_b32 s4, s42, 29
	s_add_i32 s4, s82, s4
	s_ashr_i32 s5, s4, 3
	s_and_b32 s4, s4, -8
	s_sub_i32 s4, s82, s4
	s_cmp_lt_i32 s4, 0
	s_movk_i32 s43, 0x161
	s_cselect_b32 s6, s43, 0x160
	s_mul_i32 s4, s4, s6
	s_add_i32 s4, s4, s5
	s_mul_hi_i32 s5, s4, 0x2e8ba2e9
	s_lshr_b32 s6, s5, 31
	s_ashr_i32 s5, s5, 4
	s_add_i32 s5, s5, s6
	s_lshl_b32 s6, s5, 2
	s_mulk_i32 s5, 0x58
	s_sub_i32 s5, s4, s5
	s_bfe_i32 s4, s5, 0x80000
	s_bfe_u32 s4, s4, 0x2000d
	s_add_i32 s7, s5, s4
	s_bfe_i32 s4, s7, 0x80000
	s_and_b32 s7, s7, 0xfc
	s_sub_i32 s5, s5, s7
	s_sext_i32_i16 s4, s4
	s_sext_i32_i8 s5, s5
	v_lshrrev_b32_e32 v5, 2, v3
	v_lshlrev_b32_e32 v6, 1, v3
	v_and_b32_e32 v1, 0xc0, v1
	s_lshr_b32 s4, s4, 2
	s_add_i32 s28, s6, s5
	v_and_b32_e32 v5, 4, v5
	v_and_b32_e32 v6, 24, v6
	v_sub_u32_e32 v0, v0, v1
	s_ashr_i32 s29, s28, 31
	s_bfe_i64 s[10:11], s[4:5], 0x100000
	v_or3_b32 v4, v4, v5, v6
	v_lshlrev_b32_e32 v5, 5, v12
	v_ashrrev_i16_sdwa v0, v2, sext(v0) dst_sel:DWORD dst_unused:UNUSED_PAD src0_sel:DWORD src1_sel:BYTE_0
	s_lshl_b64 s[6:7], s[28:29], 19
	s_lshl_b64 s[10:11], s[10:11], 19
	v_and_b32_e32 v5, 32, v5
	v_bfe_i32 v14, v0, 0, 16
	s_add_u32 s34, s40, s10
	v_add_lshl_u32 v0, v5, v14, 1
	s_addc_u32 s35, s41, s11
	s_add_i32 s29, s33, 0
	v_lshl_add_u32 v132, v4, 11, v0
	s_add_i32 m0, s29, 0x10000
	v_lshl_add_u32 v134, v3, 11, v0
	global_load_lds_dwordx4 v132, s[34:35]
	s_add_i32 m0, s29, 0x12000
	s_add_u32 s10, s34, 0x40000
	global_load_lds_dwordx4 v128, s[34:35]
	s_addc_u32 s11, s35, 0
	s_add_i32 m0, s29, 0x14000
	v_mov_b32_e32 v133, 0
	global_load_lds_dwordx4 v132, s[10:11]
	s_add_i32 m0, s29, 0x16000
	s_add_u32 s30, s2, s6
	s_addc_u32 s31, s3, s7
	s_add_i32 s44, s29, 0x2000
	global_load_lds_dwordx4 v128, s[10:11]
	s_mov_b32 m0, s29
	s_add_u32 s6, s30, 0x40000
	global_load_lds_dwordx4 v134, s[30:31]
	s_mov_b32 m0, s44
	s_addc_u32 s7, s31, 0
	s_add_i32 s45, s29, 0x4000
	global_load_lds_dwordx4 v130, s[30:31]
	s_mov_b32 m0, s45
	s_add_i32 s46, s29, 0x6000
	global_load_lds_dwordx4 v134, s[6:7]
	s_mov_b32 m0, s46
	v_readlane_b32 s5, v244, 18
	global_load_lds_dwordx4 v130, s[6:7]
	v_mov_b32_e32 v129, v133
	v_mov_b32_e32 v135, v133
	v_mov_b32_e32 v131, v133
	s_cmp_eq_u32 s5, 1
	s_mov_b32 s47, 0
	v_lshl_add_u64 v[4:5], s[34:35], 0, v[132:133]
	v_lshl_add_u64 v[2:3], s[34:35], 0, v[128:129]
	v_lshl_add_u64 v[0:1], s[30:31], 0, v[134:135]
	s_cselect_b64 s[6:7], -1, 0
	s_cmp_lg_u32 s5, 1
	v_lshl_add_u64 v[6:7], s[30:31], 0, v[130:131]
	s_cbranch_scc1 .LBB0_144
	s_barrier
